# in-proj epilogue: all 8 row-scale loads of the plain-column variant issued together (v73 + the 8th)
# baseline (speedup 1.0000x reference)
; __device__ __forceinline__ unsigned cvt_pk_bf16(float lo, float hi) { unsigned r; asm volatile("v_cvt_pk_bf16_f32 %0, %1, %2" : "=v"(r) : "v"(lo), "v"(hi)); return r; }
;     __device__ __forceinline__ void operator()(const f32x4 (&acc)[2][2][4][2], const Unit& u, int wr, int wc, int fr, int fq) const {
;     ...
;         const bool act = u.pn >= 6, st = u.pn >= 10;
; #pragma unroll
;         for (int ai = 0; ai < 2; ++ai)
; #pragma unroll
;             for (int m = 0; m < 4; ++m) {
;                 const int row = row0 + ai * HALF + m * 16; const float rs = r1[row];
;                 bf16_t* rowp = O + (size_t)row * PROJ_LD + col0; float s1 = 0.f, s2 = 0.f;
; #pragma unroll
;                 for (int bj = 0; bj < 2; ++bj) {
;                     f32x4 v0 = acc[ai][bj][m][0] * rs, v1 = acc[ai][bj][m][1] * rs;
;                     if (act) {
; #pragma unroll
;                         for (int j = 0; j < 4; ++j) { v0[j] = gelu_tanh(v0[j]); v1[j] = gelu_tanh(v1[j]); }
;                     }
;                     if (st) {
; #pragma unroll
;                         for (int j = 0; j < 4; ++j) { s1 += v0[j] + v1[j]; s2 += v0[j] * v0[j] + v1[j] * v1[j]; }
;                     }
;                     u32x4 w; w.x = cvt_pk_bf16(v0[0], v0[1]); w.y = cvt_pk_bf16(v0[2], v0[3]); w.z = cvt_pk_bf16(v1[0], v1[1]); w.w = cvt_pk_bf16(v1[2], v1[3]);
;                     __builtin_nontemporal_store(w, (u32x4*)(rowp + bj * HALF));
.LBB0_243:
	v_lshl_add_u64 v[128:129], v[178:179], 2, s[46:47]
	global_load_dword v130, v[128:129], off
	global_load_dword v246, v[128:129], off offset:64
	global_load_dword v248, v[128:129], off offset:128
	global_load_dword v250, v[128:129], off offset:192
	global_load_dword v252, v[128:129], off offset:512
	global_load_dword v254, v[128:129], off offset:576
	global_load_dword v152, v[128:129], off offset:640
	global_load_dword v247, v[128:129], off offset:704
	s_nop 0
	s_cmp_lg_u32 s66, 5
	s_cselect_b64 s[8:9], -1, 0
	s_cmp_eq_u32 s66, 5
	s_waitcnt vmcnt(0)
	v_pk_mul_f32 v[136:137], v[126:127], v[130:131] op_sel_hi:[1,0]
	v_pk_mul_f32 v[138:139], v[124:125], v[130:131] op_sel_hi:[1,0]
	v_pk_mul_f32 v[140:141], v[122:123], v[130:131] op_sel_hi:[1,0]
	v_pk_mul_f32 v[142:143], v[120:121], v[130:131] op_sel_hi:[1,0]
	s_cbranch_scc1 .LBB0_245
	v_mul_f32_e32 v132, v142, v142
	v_fma_f32 v132, v132, s85, 1.0
	v_mul_f32_e32 v131, v138, v138
	v_mul_f32_e32 v132, v142, v132
	v_fma_f32 v131, v131, s85, 1.0
	v_mul_f32_e32 v132, 0xc0135761, v132
	v_mul_f32_e32 v131, v138, v131
	v_exp_f32_e32 v133, v132
	v_mul_f32_e32 v132, v139, v139
	v_mul_f32_e32 v131, 0xc0135761, v131
	v_fma_f32 v132, v132, s85, 1.0
	v_exp_f32_e32 v131, v131
	v_mul_f32_e32 v132, v139, v132
	v_mul_f32_e32 v132, 0xc0135761, v132
	v_exp_f32_e32 v135, v132
	v_add_f32_e32 v131, 1.0, v131
	v_rcp_f32_e32 v132, v131
	v_add_f32_e32 v131, 1.0, v133
	v_rcp_f32_e32 v134, v131
	v_add_f32_e32 v131, 1.0, v135
	v_mul_f32_e32 v135, v136, v136
	v_fma_f32 v135, v135, s85, 1.0
	v_mul_f32_e32 v144, v140, v140
	v_mul_f32_e32 v135, v136, v135
	v_fma_f32 v144, v144, s85, 1.0
	v_mul_f32_e32 v135, 0xc0135761, v135
	v_mul_f32_e32 v144, v140, v144
	v_exp_f32_e32 v135, v135
	v_mul_f32_e32 v144, 0xc0135761, v144
	v_exp_f32_e32 v145, v144
	v_rcp_f32_e32 v133, v131
	v_add_f32_e32 v135, 1.0, v135
	v_rcp_f32_e32 v144, v135
	v_add_f32_e32 v135, 1.0, v145
	v_mul_f32_e32 v145, v137, v137
	v_mul_f32_e32 v131, v143, v143
	v_fma_f32 v145, v145, s85, 1.0
	v_mul_f32_e32 v146, v141, v141
	v_fma_f32 v131, v131, s85, 1.0
	v_mul_f32_e32 v145, v137, v145
	v_fma_f32 v146, v146, s85, 1.0
	v_mul_f32_e32 v131, v143, v131
	v_mul_f32_e32 v145, 0xc0135761, v145
	v_mul_f32_e32 v146, v141, v146
	v_mul_f32_e32 v131, 0xc0135761, v131
	v_exp_f32_e32 v145, v145
	v_mul_f32_e32 v146, 0xc0135761, v146
	v_exp_f32_e32 v131, v131
	v_exp_f32_e32 v147, v146
	v_rcp_f32_e32 v146, v135
	v_add_f32_e32 v135, 1.0, v145
	v_add_f32_e32 v131, 1.0, v131
	v_rcp_f32_e32 v145, v135
	v_add_f32_e32 v135, 1.0, v147
	v_rcp_f32_e32 v147, v135
	v_rcp_f32_e32 v135, v131
	v_pk_mul_f32 v[136:137], v[136:137], v[144:145]
	v_pk_mul_f32 v[138:139], v[138:139], v[132:133]
	v_pk_mul_f32 v[140:141], v[140:141], v[146:147]
	v_pk_mul_f32 v[142:143], v[142:143], v[134:135]

;     __device__ __forceinline__ void operator()(const f32x4 (&acc)[2][2][4][2], const Unit& u, int wr, int wc, int fr, int fq) const {
;     ...
;                 const int row = row0 + ai * HALF + m * 16; const float rs = r1[row];
;                 bf16_t* rowp = O + (size_t)row * PROJ_LD + col0; float s1 = 0.f, s2 = 0.f;
; #pragma unroll
;                 for (int bj = 0; bj < 2; ++bj) {
;                     f32x4 v0 = acc[ai][bj][m][0] * rs, v1 = acc[ai][bj][m][1] * rs;
;                     if (act) {
; #pragma unroll
;                         for (int j = 0; j < 4; ++j) { v0[j] = gelu_tanh(v0[j]); v1[j] = gelu_tanh(v1[j]); }
;                     }
.LBB0_362:
	v_mov_b32_e32 v128, v247
	s_and_b64 vcc, exec, s[6:7]
	s_nop 0
	v_pk_mul_f32 v[134:135], v[14:15], v[128:129] op_sel_hi:[1,0]
	v_pk_mul_f32 v[138:139], v[12:13], v[128:129] op_sel_hi:[1,0]
	v_pk_mul_f32 v[136:137], v[10:11], v[128:129] op_sel_hi:[1,0]
	v_pk_mul_f32 v[140:141], v[8:9], v[128:129] op_sel_hi:[1,0]
	s_cbranch_vccnz .LBB0_364
	v_mul_f32_e32 v130, v140, v140
	v_fma_f32 v130, v130, s85, 1.0
	v_mul_f32_e32 v129, v138, v138
	v_mul_f32_e32 v130, v140, v130
	v_fma_f32 v129, v129, s85, 1.0
	v_mul_f32_e32 v130, 0xc0135761, v130
	v_mul_f32_e32 v129, v138, v129
	s_waitcnt lgkmcnt(1)
	v_exp_f32_e32 v131, v130
	v_mul_f32_e32 v130, v139, v139
	v_mul_f32_e32 v129, 0xc0135761, v129
	v_fma_f32 v130, v130, s85, 1.0
	v_exp_f32_e32 v129, v129
	v_mul_f32_e32 v130, v139, v130
	v_mul_f32_e32 v130, 0xc0135761, v130
	s_waitcnt lgkmcnt(0)
	v_exp_f32_e32 v133, v130
	v_add_f32_e32 v129, 1.0, v129
	v_rcp_f32_e32 v130, v129
	v_add_f32_e32 v129, 1.0, v131
	v_rcp_f32_e32 v132, v129
	v_add_f32_e32 v129, 1.0, v133
	v_mul_f32_e32 v133, v134, v134
	v_fma_f32 v133, v133, s85, 1.0
	v_mul_f32_e32 v142, v136, v136
	v_mul_f32_e32 v133, v134, v133
	v_fma_f32 v142, v142, s85, 1.0
	v_mul_f32_e32 v133, 0xc0135761, v133
	v_mul_f32_e32 v142, v136, v142
	v_exp_f32_e32 v133, v133
	v_mul_f32_e32 v142, 0xc0135761, v142
	v_exp_f32_e32 v143, v142
	v_rcp_f32_e32 v131, v129
	v_add_f32_e32 v133, 1.0, v133
	v_rcp_f32_e32 v142, v133
	v_add_f32_e32 v133, 1.0, v143
	v_mul_f32_e32 v143, v135, v135
	v_mul_f32_e32 v129, v141, v141
	v_fma_f32 v143, v143, s85, 1.0
	v_mul_f32_e32 v144, v137, v137
	v_fma_f32 v129, v129, s85, 1.0
	v_mul_f32_e32 v143, v135, v143
	v_fma_f32 v144, v144, s85, 1.0
	v_mul_f32_e32 v129, v141, v129
	v_mul_f32_e32 v143, 0xc0135761, v143
	v_mul_f32_e32 v144, v137, v144
	v_mul_f32_e32 v129, 0xc0135761, v129
	v_exp_f32_e32 v143, v143
	v_mul_f32_e32 v144, 0xc0135761, v144
	v_exp_f32_e32 v129, v129
	v_exp_f32_e32 v145, v144
	v_rcp_f32_e32 v144, v133
	v_add_f32_e32 v133, 1.0, v143
	v_add_f32_e32 v129, 1.0, v129
	v_rcp_f32_e32 v143, v133
	v_add_f32_e32 v133, 1.0, v145
	v_rcp_f32_e32 v145, v133
	v_rcp_f32_e32 v133, v129
	v_pk_mul_f32 v[134:135], v[134:135], v[142:143]
	v_pk_mul_f32 v[138:139], v[138:139], v[130:131]
	v_pk_mul_f32 v[136:137], v[136:137], v[144:145]
	v_pk_mul_f32 v[140:141], v[140:141], v[132:133]
